# v38 + rmsnorm+mod copy at LBB0_1728: all 16 row loads hoisted to the top with counted vmcnt
# speedup vs baseline: 1.0047x; 1.0047x over previous
;     ...
;     for (int r = rbeg + gw; r < nrows; r += nw) {
;         const float* xp = (r < T_LAT) ? xlat + (size_t)r * DM : xctx + (size_t)(r - T_LAT) * DM;
;         const int m = (r < T_LAT) ? (r >> 12) : 8;
;         const float* mv = p.modv + ((size_t)layer * 9 + m) * 6144 + shift_i * 1024;
;         f32x4 v[4];
;         float ss = 0.f;
; #pragma unroll
;         for (int i = 0; i < 4; ++i) {
;             v[i] = *reinterpret_cast<const f32x4*>(xp + (i * 64 + lane) * 4);
;             ss += v[i][0] * v[i][0] + v[i][1] * v[i][1] + v[i][2] * v[i][2] + v[i][3] * v[i][3];
;         }
; #pragma unroll
;         for (int o = 32; o >= 1; o >>= 1) ss += __shfl_xor(ss, o);
;         const float rstd = rsqrtf(ss * (1.0f / 1024.0f) + EPSV);
;         bf16_t* hp = p.hbuf + (size_t)r * DM;
; #pragma unroll
;         for (int i = 0; i < 4; ++i) {
;             const int col = (i * 64 + lane) * 4;
;             f32x4 gg = *reinterpret_cast<const f32x4*>(g + col);
;             f32x4 sh = *reinterpret_cast<const f32x4*>(mv + col);
;             f32x4 sc = *reinterpret_cast<const f32x4*>(mv + 1024 + col);
;             float o0 = v[i][0] * rstd * gg[0] * (1.f + sc[0]) + sh[0];
;             float o1 = v[i][1] * rstd * gg[1] * (1.f + sc[1]) + sh[1];
;             float o2 = v[i][2] * rstd * gg[2] * (1.f + sc[2]) + sh[2];
;             float o3 = v[i][3] * rstd * gg[3] * (1.f + sc[3]) + sh[3];
;             u32x2 o = {pack2(o0, o1), pack2(o2, o3)};
;             *reinterpret_cast<u32x2*>(hp + col) = o;
;         }
;     }
.LBB0_1728:
	s_or_b64 exec, exec, s[14:15]
	v_mov_b32_e32 v31, v0
	v_lshl_add_u64 v[2:3], v[2:3], 0, v[30:31]
	global_load_dwordx4 v[14:17], v[2:3], off
	global_load_dwordx4 v[10:13], v[2:3], off offset:1024
	global_load_dwordx4 v[192:195], v[2:3], off offset:2048
	global_load_dwordx4 v[196:199], v[2:3], off offset:3072
	global_load_dwordx4 v[200:203], v[24:25], off
	global_load_dwordx4 v[204:207], v[24:25], off offset:1024
	global_load_dwordx4 v[208:211], v[24:25], off offset:2048
	global_load_dwordx4 v[212:215], v[24:25], off offset:3072
	v_min_i32_e32 v4, 0x8000, v22
	v_ashrrev_i32_e32 v4, 12, v4
	v_readlane_b32 s64, v254, 6
	v_ashrrev_i32_e32 v5, 31, v4
	v_readlane_b32 s70, v254, 12
	v_readlane_b32 s71, v254, 13
	v_lshl_add_u64 v[4:5], v[4:5], 0, s[20:21]
	v_mov_b32_e32 v37, v0
	v_mov_b64_e32 v[6:7], s[70:71]
	v_mad_u64_u32 v[18:19], s[0:1], v4, s74, v[6:7]
	v_mad_i32_i24 v19, v5, s74, v19
	v_mov_b32_e32 v243, v0
	v_mov_b32_e32 v242, v32
	v_lshl_add_u64 v[240:241], v[18:19], 0, v[30:31]
	v_lshl_add_u64 v[248:249], v[18:19], 0, s[90:91]
	global_load_dwordx4 v[216:219], v[240:241], off
	global_load_dwordx4 v[220:223], v[240:241], off offset:1024
	global_load_dwordx4 v[224:227], v[240:241], off offset:2048
	global_load_dwordx4 v[228:231], v[240:241], off offset:3072
	v_lshl_add_u64 v[240:241], v[248:249], 0, v[30:31]
	global_load_dwordx4 v[54:57], v[240:241], off
	v_lshl_add_u64 v[240:241], v[248:249], 0, v[242:243]
	global_load_dwordx4 v[232:235], v[240:241], off
	v_mov_b32_e32 v242, v34
	v_lshl_add_u64 v[240:241], v[248:249], 0, v[242:243]
	global_load_dwordx4 v[236:239], v[240:241], off
	v_lshl_add_u64 v[240:241], v[248:249], 0, v[36:37]
	global_load_dwordx4 v[244:247], v[240:241], off
	v_lshl_add_u64 v[22:23], v[22:23], 0, s[38:39]
	v_lshl_add_u64 v[28:29], v[28:29], 0, s[52:53]
	v_readlane_b32 s65, v254, 7
	v_readlane_b32 s66, v254, 8
	v_readlane_b32 s67, v254, 9
	v_readlane_b32 s68, v254, 10
	v_readlane_b32 s69, v254, 11
	s_waitcnt vmcnt(14)
	v_mov_b32_e32 v6, v15
	v_mov_b32_e32 v7, v11
	v_mov_b32_e32 v4, v14
	v_mov_b32_e32 v5, v10
	v_pk_mul_f32 v[6:7], v[6:7], v[6:7]
	s_nop 0
	v_pk_fma_f32 v[4:5], v[4:5], v[4:5], v[6:7]
	v_mov_b32_e32 v6, v16
	v_mov_b32_e32 v7, v12
	v_pk_fma_f32 v[4:5], v[6:7], v[6:7], v[4:5]
	v_mov_b32_e32 v6, v17
	v_mov_b32_e32 v7, v13
	v_pk_fma_f32 v[40:41], v[6:7], v[6:7], v[4:5]
	s_waitcnt vmcnt(12)
	v_mov_b32_e32 v6, v192
	v_mov_b32_e32 v7, v193
	v_mov_b32_e32 v8, v194
	v_mov_b32_e32 v9, v195
	v_mov_b32_e32 v2, v196
	v_mov_b32_e32 v3, v197
	v_mov_b32_e32 v4, v198
	v_mov_b32_e32 v5, v199
	v_add_f32_e32 v33, v40, v41
	v_lshlrev_b64 v[40:41], 11, v[20:21]
	v_lshl_add_u64 v[40:41], v[26:27], 0, v[40:41]
	v_mov_b32_e32 v44, v7
	v_mov_b32_e32 v45, v3
	v_mov_b32_e32 v42, v6
	v_mov_b32_e32 v43, v2
	v_pk_mul_f32 v[44:45], v[44:45], v[44:45]
	s_nop 0
	v_pk_fma_f32 v[42:43], v[42:43], v[42:43], v[44:45]
	v_mov_b32_e32 v44, v8
	v_mov_b32_e32 v45, v4
	v_pk_fma_f32 v[42:43], v[44:45], v[44:45], v[42:43]
	v_mov_b32_e32 v44, v9
	v_mov_b32_e32 v45, v5
	v_pk_fma_f32 v[42:43], v[44:45], v[44:45], v[42:43]
	s_nop 0
	v_add_f32_e32 v33, v33, v42
	v_add_f32_e32 v33, v33, v43
	ds_bpermute_b32 v35, v1, v33
	s_waitcnt lgkmcnt(0)
	v_add_f32_e32 v33, v33, v35
	ds_bpermute_b32 v35, v39, v33
	s_waitcnt lgkmcnt(0)
	v_add_f32_e32 v33, v33, v35
	ds_bpermute_b32 v35, v46, v33
	s_waitcnt lgkmcnt(0)
	v_add_f32_e32 v33, v33, v35
	ds_bpermute_b32 v35, v47, v33
	s_waitcnt lgkmcnt(0)
	v_add_f32_e32 v33, v33, v35
	ds_bpermute_b32 v35, v48, v33
	s_waitcnt lgkmcnt(0)
	v_add_f32_e32 v33, v33, v35
	ds_bpermute_b32 v35, v49, v33
	s_waitcnt lgkmcnt(0)
	v_add_f32_e32 v33, v33, v35
	v_fmamk_f32 v33, v33, 0x3a800000, v177
	v_cmp_gt_f32_e32 vcc, s93, v33
	v_mul_f32_e32 v35, 0x4b800000, v33
	s_nop 0
	v_cndmask_b32_e32 v33, v33, v35, vcc
	v_rsq_f32_e32 v33, v33
	s_nop 0
	v_mul_f32_e32 v35, 0x45800000, v33
	v_cndmask_b32_e32 v38, v33, v35, vcc
	v_pk_mul_f32 v[14:15], v[14:15], v[38:39] op_sel_hi:[1,0]
	v_pk_mul_f32 v[16:17], v[16:17], v[38:39] op_sel_hi:[1,0]
	v_mov_b32_e32 v33, v0
	v_pk_mul_f32 v[10:11], v[10:11], v[38:39] op_sel_hi:[1,0]
	v_pk_mul_f32 v[12:13], v[12:13], v[38:39] op_sel_hi:[1,0]
	v_mov_b32_e32 v35, v0
	v_pk_mul_f32 v[6:7], v[6:7], v[38:39] op_sel_hi:[1,0]
	v_pk_mul_f32 v[8:9], v[8:9], v[38:39] op_sel_hi:[1,0]
	v_pk_mul_f32 v[2:3], v[2:3], v[38:39] op_sel_hi:[1,0]
	v_pk_mul_f32 v[4:5], v[4:5], v[38:39] op_sel_hi:[1,0]
	v_cmp_lt_i32_e32 vcc, s94, v22
	s_or_b64 s[12:13], vcc, s[12:13]
	s_waitcnt vmcnt(0)
	v_pk_mul_f32 v[14:15], v[200:201], v[14:15]
	v_pk_mul_f32 v[16:17], v[202:203], v[16:17]
	v_pk_add_f32 v[50:51], v[54:55], 1.0 op_sel_hi:[1,0]
	s_nop 0
	v_pk_fma_f32 v[14:15], v[50:51], v[14:15], v[216:217]
	v_pk_add_f32 v[18:19], v[56:57], 1.0 op_sel_hi:[1,0]
	v_cvt_pk_bf16_f32 v14, v14, v15
	v_pk_fma_f32 v[16:17], v[18:19], v[16:17], v[218:219]
	v_pk_mul_f32 v[10:11], v[204:205], v[10:11]
	v_cvt_pk_bf16_f32 v15, v16, v17
	global_store_dwordx2 v[40:41], v[14:15], off
	v_pk_mul_f32 v[12:13], v[206:207], v[12:13]
	v_pk_add_f32 v[18:19], v[232:233], 1.0 op_sel_hi:[1,0]
	s_nop 0
	v_pk_fma_f32 v[10:11], v[18:19], v[10:11], v[220:221]
	v_pk_add_f32 v[14:15], v[234:235], 1.0 op_sel_hi:[1,0]
	v_cvt_pk_bf16_f32 v10, v10, v11
	v_pk_fma_f32 v[12:13], v[14:15], v[12:13], v[222:223]
	v_pk_mul_f32 v[6:7], v[208:209], v[6:7]
	v_cvt_pk_bf16_f32 v11, v12, v13
	global_store_dwordx2 v[40:41], v[10:11], off offset:512
	v_pk_mul_f32 v[8:9], v[210:211], v[8:9]
	v_pk_add_f32 v[10:11], v[236:237], 1.0 op_sel_hi:[1,0]
	s_nop 0
	v_pk_fma_f32 v[6:7], v[10:11], v[6:7], v[224:225]
	v_pk_add_f32 v[10:11], v[238:239], 1.0 op_sel_hi:[1,0]
	v_cvt_pk_bf16_f32 v6, v6, v7
	v_pk_fma_f32 v[8:9], v[10:11], v[8:9], v[226:227]
	v_pk_mul_f32 v[2:3], v[2:3], v[212:213]
	v_cvt_pk_bf16_f32 v7, v8, v9
	global_store_dwordx2 v[40:41], v[6:7], off offset:1024
	v_pk_mul_f32 v[4:5], v[4:5], v[214:215]
	v_pk_add_f32 v[6:7], v[244:245], 1.0 op_sel_hi:[1,0]
	s_nop 0
	v_pk_fma_f32 v[2:3], v[2:3], v[6:7], v[228:229]
	v_pk_add_f32 v[6:7], v[246:247], 1.0 op_sel_hi:[1,0]
	v_cvt_pk_bf16_f32 v2, v2, v3
	v_pk_fma_f32 v[4:5], v[4:5], v[6:7], v[230:231]
	s_nop 0
	v_cvt_pk_bf16_f32 v3, v4, v5
	global_store_dwordx2 v[40:41], v[2:3], off offset:1536
	s_andn2_b64 exec, exec, s[12:13]
	s_cbranch_execz .LBB0_1731
